# GEMM tile prologue: the 128 accumulator-clearing v_mov_b32 per tile replaced by 64 v_mov_b64 (all four GEMM phases)
# baseline (speedup 1.0000x reference)
; template <class Epi>
; __device__ __forceinline__ void gemm_phase(LAS unsigned char* lds, const Gemm g, const StaticOrder& S, const Epi& E) {
;     ...
;         const char* nA = has_next ? (const char*)g.A + (size_t)npm * tstep + (size_t)nk0 * kstep : cA; const char* nB = has_next ? (const char*)g.Bt + (size_t)npn * tstep + (size_t)nk0 * kstep : cB;
;         const int nt = cnk;
;         for (int t = 0; t < nt; t += 2) {
;             const bool last = (t == nt - 2);
;             const char* a1 = cA + (size_t)(t + 1) * kstep;
;             const char* a2 = last ? nA : cA + (size_t)(t + 2) * kstep; const char* b2 = last ? nB : cB + (size_t)(t + 2) * kstep;
;     ...
;         for (int a = 0; a < 2; ++a)
; #pragma unroll
;             for (int b = 0; b < 2; ++b)
; #pragma unroll
;                 for (int m = 0; m < 4; ++m)
; #pragma unroll
;                     for (int n = 0; n < 2; ++n) acc[a][b][m][n] = (f32x4){0.f, 0.f, 0.f, 0.f};
.LBB0_566:
	s_ashr_i32 s61, s60, 31
	s_lshl_b64 s[30:31], s[60:61], 19
	s_add_u32 s66, s1, s30
	s_addc_u32 s67, s0, s31
	s_ashr_i32 s63, s62, 31
	s_lshl_b64 s[30:31], s[62:63], 19
	s_add_u32 s68, s4, s30
	s_addc_u32 s69, s3, s31
	s_cmp_eq_u32 s29, 0
	s_cbranch_scc1 .LBB0_569
	s_and_b64 s[30:31], s[70:71], exec
	s_cselect_b32 s33, s67, s51
	s_cselect_b32 s38, s66, s50
	s_cselect_b32 s39, s69, s53
	s_cselect_b32 s61, s68, s52
	s_add_i32 s63, s29, -2
	s_add_u32 s72, s52, 0x100
	s_addc_u32 s73, s53, 0
	s_add_u32 s50, s50, 0x40080
	v_mov_b64_e32 v[8:9], 0
	v_mov_b64_e32 v[10:11], 0
	v_mov_b64_e32 v[12:13], 0
	v_mov_b64_e32 v[14:15], 0
	v_mov_b64_e32 v[16:17], 0
	v_mov_b64_e32 v[18:19], 0
	v_mov_b64_e32 v[20:21], 0
	v_mov_b64_e32 v[22:23], 0
	v_mov_b64_e32 v[24:25], 0
	v_mov_b64_e32 v[26:27], 0
	v_mov_b64_e32 v[28:29], 0
	v_mov_b64_e32 v[30:31], 0
	v_mov_b64_e32 v[32:33], 0
	v_mov_b64_e32 v[34:35], 0
	v_mov_b64_e32 v[36:37], 0
	v_mov_b64_e32 v[38:39], 0
	v_mov_b64_e32 v[40:41], 0
	v_mov_b64_e32 v[42:43], 0
	v_mov_b64_e32 v[44:45], 0
	v_mov_b64_e32 v[46:47], 0
	v_mov_b64_e32 v[48:49], 0
	v_mov_b64_e32 v[50:51], 0
	v_mov_b64_e32 v[52:53], 0
	v_mov_b64_e32 v[54:55], 0
	v_mov_b64_e32 v[56:57], 0
	v_mov_b64_e32 v[58:59], 0
	v_mov_b64_e32 v[60:61], 0
	v_mov_b64_e32 v[62:63], 0
	v_mov_b64_e32 v[64:65], 0
	v_mov_b64_e32 v[66:67], 0
	v_mov_b64_e32 v[68:69], 0
	v_mov_b64_e32 v[70:71], 0
	v_mov_b64_e32 v[72:73], 0
	v_mov_b64_e32 v[74:75], 0
	v_mov_b64_e32 v[76:77], 0
	v_mov_b64_e32 v[78:79], 0
	v_mov_b64_e32 v[80:81], 0
	v_mov_b64_e32 v[82:83], 0
	v_mov_b64_e32 v[84:85], 0
	v_mov_b64_e32 v[86:87], 0
	v_mov_b64_e32 v[88:89], 0
	v_mov_b64_e32 v[90:91], 0
	v_mov_b64_e32 v[92:93], 0
	v_mov_b64_e32 v[94:95], 0
	v_mov_b64_e32 v[96:97], 0
	v_mov_b64_e32 v[98:99], 0
	v_mov_b64_e32 v[100:101], 0
	v_mov_b64_e32 v[102:103], 0
	v_mov_b64_e32 v[104:105], 0
	v_mov_b64_e32 v[106:107], 0
	v_mov_b64_e32 v[108:109], 0
	v_mov_b64_e32 v[110:111], 0
	v_mov_b64_e32 v[112:113], 0
	v_mov_b64_e32 v[114:115], 0
	v_mov_b64_e32 v[116:117], 0
	v_mov_b64_e32 v[118:119], 0
	v_mov_b64_e32 v[120:121], 0
	v_mov_b64_e32 v[122:123], 0
	v_mov_b64_e32 v[124:125], 0
	v_mov_b64_e32 v[126:127], 0
	v_mov_b64_e32 v[128:129], 0
	v_mov_b64_e32 v[130:131], 0
	v_mov_b64_e32 v[132:133], 0
	v_mov_b64_e32 v[134:135], 0
	s_addc_u32 s51, s51, 0
	s_mov_b32 s52, 0

; template <class Epi>
; __device__ __forceinline__ void gemm_phase(LAS unsigned char* lds, const Gemm g, const StaticOrder& S, const Epi& E) {
;     ...
;         const char* nA = has_next ? (const char*)g.A + (size_t)npm * tstep + (size_t)nk0 * kstep : cA; const char* nB = has_next ? (const char*)g.Bt + (size_t)npn * tstep + (size_t)nk0 * kstep : cB;
;         const int nt = cnk;
;         for (int t = 0; t < nt; t += 2) {
;             const bool last = (t == nt - 2);
;             const char* a1 = cA + (size_t)(t + 1) * kstep;
;             const char* a2 = last ? nA : cA + (size_t)(t + 2) * kstep; const char* b2 = last ? nB : cB + (size_t)(t + 2) * kstep;
;     ...
;         for (int a = 0; a < 2; ++a)
; #pragma unroll
;             for (int b = 0; b < 2; ++b)
; #pragma unroll
;                 for (int m = 0; m < 4; ++m)
; #pragma unroll
;                     for (int n = 0; n < 2; ++n) acc[a][b][m][n] = (f32x4){0.f, 0.f, 0.f, 0.f};
.LBB0_1487:
	s_ashr_i32 s49, s48, 31
	s_lshl_b64 s[30:31], s[48:49], 19
	s_add_u32 s49, s53, s30
	s_addc_u32 s61, s52, s31
	s_lshl_b64 s[30:31], s[6:7], 7
	s_add_u32 s62, s49, s30
	s_addc_u32 s63, s61, s31
	s_ashr_i32 s61, s60, 31
	s_lshl_b64 s[64:65], s[60:61], 19
	s_add_u32 s49, s39, s64
	s_addc_u32 s61, s38, s65
	s_add_u32 s64, s49, s30
	s_addc_u32 s65, s61, s31
	s_cmp_lt_i32 s90, 1
	s_cbranch_scc1 .LBB0_1491
	s_and_b64 s[30:31], s[70:71], exec
	s_cselect_b32 s49, s63, s73
	s_cselect_b32 s61, s62, s72
	s_cselect_b32 s67, s65, s75
	s_cselect_b32 s69, s64, s74
	s_add_i32 s91, s90, -2
	s_mov_b64 s[50:51], s[96:97]
	s_add_u32 s96, s74, 0x100
	v_mov_b64_e32 v[8:9], 0
	v_mov_b64_e32 v[10:11], 0
	v_mov_b64_e32 v[12:13], 0
	v_mov_b64_e32 v[14:15], 0
	v_mov_b64_e32 v[16:17], 0
	v_mov_b64_e32 v[18:19], 0
	v_mov_b64_e32 v[20:21], 0
	v_mov_b64_e32 v[22:23], 0
	v_mov_b64_e32 v[24:25], 0
	v_mov_b64_e32 v[26:27], 0
	v_mov_b64_e32 v[28:29], 0
	v_mov_b64_e32 v[30:31], 0
	v_mov_b64_e32 v[32:33], 0
	v_mov_b64_e32 v[34:35], 0
	v_mov_b64_e32 v[36:37], 0
	v_mov_b64_e32 v[38:39], 0
	v_mov_b64_e32 v[40:41], 0
	v_mov_b64_e32 v[42:43], 0
	v_mov_b64_e32 v[44:45], 0
	v_mov_b64_e32 v[46:47], 0
	v_mov_b64_e32 v[48:49], 0
	v_mov_b64_e32 v[50:51], 0
	v_mov_b64_e32 v[52:53], 0
	v_mov_b64_e32 v[54:55], 0
	v_mov_b64_e32 v[56:57], 0
	v_mov_b64_e32 v[58:59], 0
	v_mov_b64_e32 v[60:61], 0
	v_mov_b64_e32 v[62:63], 0
	v_mov_b64_e32 v[64:65], 0
	v_mov_b64_e32 v[66:67], 0
	v_mov_b64_e32 v[68:69], 0
	v_mov_b64_e32 v[70:71], 0
	v_mov_b64_e32 v[72:73], 0
	v_mov_b64_e32 v[74:75], 0
	v_mov_b64_e32 v[76:77], 0
	v_mov_b64_e32 v[78:79], 0
	v_mov_b64_e32 v[80:81], 0
	v_mov_b64_e32 v[82:83], 0
	v_mov_b64_e32 v[84:85], 0
	v_mov_b64_e32 v[86:87], 0
	v_mov_b64_e32 v[88:89], 0
	v_mov_b64_e32 v[90:91], 0
	v_mov_b64_e32 v[92:93], 0
	v_mov_b64_e32 v[94:95], 0
	v_mov_b64_e32 v[96:97], 0
	v_mov_b64_e32 v[98:99], 0
	v_mov_b64_e32 v[100:101], 0
	v_mov_b64_e32 v[102:103], 0
	v_mov_b64_e32 v[104:105], 0
	v_mov_b64_e32 v[106:107], 0
	v_mov_b64_e32 v[108:109], 0
	v_mov_b64_e32 v[110:111], 0
	v_mov_b64_e32 v[112:113], 0
	v_mov_b64_e32 v[114:115], 0
	v_mov_b64_e32 v[116:117], 0
	v_mov_b64_e32 v[118:119], 0
	v_mov_b64_e32 v[120:121], 0
	v_mov_b64_e32 v[122:123], 0
	v_mov_b64_e32 v[124:125], 0
	v_mov_b64_e32 v[126:127], 0
	v_mov_b64_e32 v[128:129], 0
	v_mov_b64_e32 v[130:131], 0
	v_mov_b64_e32 v[132:133], 0
	v_mov_b64_e32 v[134:135], 0
	s_addc_u32 s97, s75, 0
	s_mov_b32 s94, 0

; template <class Epi>
; __device__ __forceinline__ void gemm_phase(LAS unsigned char* lds, const Gemm g, const StaticOrder& S, const Epi& E) {
;     ...
;         const char* nA = has_next ? (const char*)g.A + (size_t)npm * tstep + (size_t)nk0 * kstep : cA; const char* nB = has_next ? (const char*)g.Bt + (size_t)npn * tstep + (size_t)nk0 * kstep : cB;
;         const int nt = cnk;
;         for (int t = 0; t < nt; t += 2) {
;             const bool last = (t == nt - 2);
;             const char* a1 = cA + (size_t)(t + 1) * kstep;
;             const char* a2 = last ? nA : cA + (size_t)(t + 2) * kstep; const char* b2 = last ? nB : cB + (size_t)(t + 2) * kstep;
;     ...
;         for (int a = 0; a < 2; ++a)
; #pragma unroll
;             for (int b = 0; b < 2; ++b)
; #pragma unroll
;                 for (int m = 0; m < 4; ++m)
; #pragma unroll
;                     for (int n = 0; n < 2; ++n) acc[a][b][m][n] = (f32x4){0.f, 0.f, 0.f, 0.f};
.LBB0_1764:
	s_ashr_i32 s45, s44, 31
	s_lshl_b64 s[4:5], s[44:45], 19
	s_add_u32 s48, s53, s4
	s_addc_u32 s49, s52, s5
	s_ashr_i32 s47, s46, 31
	s_lshl_b64 s[4:5], s[46:47], 19
	s_add_u32 s54, s64, s4
	s_addc_u32 s55, s28, s5
	s_cmp_eq_u32 s1, 0
	s_cbranch_scc1 .LBB0_1760
	s_and_b64 s[4:5], s[62:63], exec
	s_cselect_b32 s4, s49, s59
	s_cselect_b32 s5, s48, s58
	s_cselect_b32 s21, s55, s61
	s_cselect_b32 s22, s54, s60
	s_add_i32 s23, s1, -2
	s_add_u32 s24, s60, 0x100
	s_addc_u32 s25, s61, 0
	s_add_u32 s58, s58, 0x40080
	v_mov_b64_e32 v[8:9], 0
	v_mov_b64_e32 v[10:11], 0
	v_mov_b64_e32 v[12:13], 0
	v_mov_b64_e32 v[14:15], 0
	v_mov_b64_e32 v[16:17], 0
	v_mov_b64_e32 v[18:19], 0
	v_mov_b64_e32 v[20:21], 0
	v_mov_b64_e32 v[22:23], 0
	v_mov_b64_e32 v[24:25], 0
	v_mov_b64_e32 v[26:27], 0
	v_mov_b64_e32 v[28:29], 0
	v_mov_b64_e32 v[30:31], 0
	v_mov_b64_e32 v[32:33], 0
	v_mov_b64_e32 v[34:35], 0
	v_mov_b64_e32 v[36:37], 0
	v_mov_b64_e32 v[38:39], 0
	v_mov_b64_e32 v[40:41], 0
	v_mov_b64_e32 v[42:43], 0
	v_mov_b64_e32 v[44:45], 0
	v_mov_b64_e32 v[46:47], 0
	v_mov_b64_e32 v[48:49], 0
	v_mov_b64_e32 v[50:51], 0
	v_mov_b64_e32 v[52:53], 0
	v_mov_b64_e32 v[54:55], 0
	v_mov_b64_e32 v[56:57], 0
	v_mov_b64_e32 v[58:59], 0
	v_mov_b64_e32 v[60:61], 0
	v_mov_b64_e32 v[62:63], 0
	v_mov_b64_e32 v[64:65], 0
	v_mov_b64_e32 v[66:67], 0
	v_mov_b64_e32 v[68:69], 0
	v_mov_b64_e32 v[70:71], 0
	v_mov_b64_e32 v[72:73], 0
	v_mov_b64_e32 v[74:75], 0
	v_mov_b64_e32 v[76:77], 0
	v_mov_b64_e32 v[78:79], 0
	v_mov_b64_e32 v[80:81], 0
	v_mov_b64_e32 v[82:83], 0
	v_mov_b64_e32 v[84:85], 0
	v_mov_b64_e32 v[86:87], 0
	v_mov_b64_e32 v[88:89], 0
	v_mov_b64_e32 v[90:91], 0
	v_mov_b64_e32 v[92:93], 0
	v_mov_b64_e32 v[94:95], 0
	v_mov_b64_e32 v[96:97], 0
	v_mov_b64_e32 v[98:99], 0
	v_mov_b64_e32 v[100:101], 0
	v_mov_b64_e32 v[102:103], 0
	v_mov_b64_e32 v[104:105], 0
	v_mov_b64_e32 v[106:107], 0
	v_mov_b64_e32 v[108:109], 0
	v_mov_b64_e32 v[110:111], 0
	v_mov_b64_e32 v[112:113], 0
	v_mov_b64_e32 v[114:115], 0
	v_mov_b64_e32 v[116:117], 0
	v_mov_b64_e32 v[118:119], 0
	v_mov_b64_e32 v[120:121], 0
	v_mov_b64_e32 v[122:123], 0
	v_mov_b64_e32 v[124:125], 0
	v_mov_b64_e32 v[126:127], 0
	v_mov_b64_e32 v[128:129], 0
	v_mov_b64_e32 v[130:131], 0
	v_mov_b64_e32 v[132:133], 0
	v_mov_b64_e32 v[134:135], 0
	s_addc_u32 s59, s59, 0
	s_mov_b32 s29, 0

; template <class Epi>
; __device__ __forceinline__ void gemm_phase(LAS unsigned char* lds, const Gemm g, const StaticOrder& S, const Epi& E) {
;     ...
;         for (int t = 0; t < nt; t += 2) {
;             const bool last = (t == nt - 2);
;             const char* a1 = cA + (size_t)(t + 1) * kstep;
;             const char* a2 = last ? nA : cA + (size_t)(t + 2) * kstep; const char* b2 = last ? nB : cB + (size_t)(t + 2) * kstep;
;     ...
; #pragma unroll
;         for (int a = 0; a < 2; ++a)
; #pragma unroll
;             for (int b = 0; b < 2; ++b)
; #pragma unroll
;                 for (int m = 0; m < 4; ++m)
; #pragma unroll
;                     for (int n = 0; n < 2; ++n) acc[a][b][m][n] = (f32x4){0.f, 0.f, 0.f, 0.f};
.LBB0_1858:
	s_add_i32 s74, s73, -2
	s_add_u32 s75, s58, 0x100
	v_mov_b64_e32 v[8:9], 0
	v_mov_b64_e32 v[10:11], 0
	v_mov_b64_e32 v[12:13], 0
	v_mov_b64_e32 v[14:15], 0
	v_mov_b64_e32 v[16:17], 0
	v_mov_b64_e32 v[18:19], 0
	v_mov_b64_e32 v[20:21], 0
	v_mov_b64_e32 v[22:23], 0
	v_mov_b64_e32 v[24:25], 0
	v_mov_b64_e32 v[26:27], 0
	v_mov_b64_e32 v[28:29], 0
	v_mov_b64_e32 v[30:31], 0
	v_mov_b64_e32 v[32:33], 0
	v_mov_b64_e32 v[34:35], 0
	v_mov_b64_e32 v[36:37], 0
	v_mov_b64_e32 v[38:39], 0
	v_mov_b64_e32 v[40:41], 0
	v_mov_b64_e32 v[42:43], 0
	v_mov_b64_e32 v[44:45], 0
	v_mov_b64_e32 v[46:47], 0
	v_mov_b64_e32 v[48:49], 0
	v_mov_b64_e32 v[50:51], 0
	v_mov_b64_e32 v[52:53], 0
	v_mov_b64_e32 v[54:55], 0
	v_mov_b64_e32 v[56:57], 0
	v_mov_b64_e32 v[58:59], 0
	v_mov_b64_e32 v[60:61], 0
	v_mov_b64_e32 v[62:63], 0
	v_mov_b64_e32 v[64:65], 0
	v_mov_b64_e32 v[66:67], 0
	v_mov_b64_e32 v[68:69], 0
	v_mov_b64_e32 v[70:71], 0
	v_mov_b64_e32 v[72:73], 0
	v_mov_b64_e32 v[74:75], 0
	v_mov_b64_e32 v[76:77], 0
	v_mov_b64_e32 v[78:79], 0
	v_mov_b64_e32 v[80:81], 0
	v_mov_b64_e32 v[82:83], 0
	v_mov_b64_e32 v[84:85], 0
	v_mov_b64_e32 v[86:87], 0
	v_mov_b64_e32 v[88:89], 0
	v_mov_b64_e32 v[90:91], 0
	v_mov_b64_e32 v[92:93], 0
	v_mov_b64_e32 v[94:95], 0
	v_mov_b64_e32 v[96:97], 0
	v_mov_b64_e32 v[98:99], 0
	v_mov_b64_e32 v[100:101], 0
	v_mov_b64_e32 v[102:103], 0
	v_mov_b64_e32 v[104:105], 0
	v_mov_b64_e32 v[106:107], 0
	v_mov_b64_e32 v[108:109], 0
	v_mov_b64_e32 v[110:111], 0
	v_mov_b64_e32 v[112:113], 0
	v_mov_b64_e32 v[114:115], 0
	v_mov_b64_e32 v[116:117], 0
	v_mov_b64_e32 v[118:119], 0
	v_mov_b64_e32 v[120:121], 0
	v_mov_b64_e32 v[122:123], 0
	v_mov_b64_e32 v[124:125], 0
	v_mov_b64_e32 v[126:127], 0
	v_mov_b64_e32 v[128:129], 0
	v_mov_b64_e32 v[130:131], 0
	v_mov_b64_e32 v[132:133], 0
	v_mov_b64_e32 v[134:135], 0
	s_addc_u32 s78, s59, 0
	s_mov_b32 s60, 0
